# GEMM phase prologues: K-tile-1 loads issued before the first prologue wait (vmcnt(8)), P4 prologue's trailing vmcnt(0) removed; on top of the stacked epilogue edits
# speedup vs baseline: 1.0048x; 1.0048x over previous
.LBB0_196:
	s_mov_b64 s[40:41], 0x80
	s_and_b32 s1, s3, 3
	s_add_i32 m0, s15, 0x18000
	v_lshl_add_u64 v[6:7], v[6:7], 0, s[40:41]
	s_lshl_b32 s56, s4, 6
	s_lshl_b32 s3, s4, 13
	s_lshl_b32 s6, s1, 12
	global_load_lds_dwordx4 v[6:7], off
	v_lshl_add_u64 v[4:5], v[4:5], 0, s[40:41]
	s_add_i32 m0, s15, 0x1a000
	s_add_i32 s57, s15, 0x8000
	s_add_i32 s58, s15, 0xa000
	global_load_lds_dwordx4 v[4:5], off
	v_lshl_add_u64 v[0:1], v[0:1], 0, s[40:41]
	s_mov_b32 m0, s57
	s_add_u32 s4, s80, 0x40080
	global_load_lds_dwordx4 v[0:1], off
	v_lshl_add_u64 v[0:1], v[2:3], 0, s[40:41]
	s_mov_b32 m0, s58
	s_addc_u32 s5, s81, 0
	global_load_lds_dwordx4 v[0:1], off
	s_add_i32 m0, s15, 0x1c000
	v_lshl_add_u64 v[0:1], s[4:5], 0, v[178:179]
	global_load_lds_dwordx4 v[0:1], off
	v_lshl_add_u64 v[0:1], s[4:5], 0, v[182:183]
	s_add_i32 m0, s15, 0x1e000
	v_and_b32_e32 v187, 15, v8
	global_load_lds_dwordx4 v[0:1], off
	v_bfe_u32 v1, v8, 4, 2
	v_lshlrev_b32_e32 v2, 4, v1
	v_lshlrev_b32_e32 v3, 2, v8
	v_lshlrev_b32_e32 v0, 3, v1
	v_lshl_or_b32 v2, v187, 6, v2
	v_and_b32_e32 v3, 32, v3
	v_bitop3_b32 v212, v2, s6, v3 bitop3:0xde
	v_cmp_gt_u32_e64 s[6:7], 2, v1
	v_cmp_eq_u32_e32 vcc, 0, v1
	v_lshl_or_b32 v1, s1, 5, v0
	v_or_b32_e32 v217, 0xfffffd00, v1
	v_lshlrev_b32_e32 v1, 14, v9
	v_and_b32_e32 v1, 0xffff8000, v1
	v_bitop3_b32 v4, v2, s3, v3 bitop3:0xde
	v_lshl_add_u32 v1, v10, 11, v1
	v_and_b32_e32 v2, 1, v9
	v_lshl_or_b32 v1, v2, 6, v1
	v_lshl_add_u32 v192, v11, 1, v1
	v_lshlrev_b32_e32 v1, 14, v12
	v_and_b32_e32 v1, 0xffff8000, v1
	s_waitcnt vmcnt(8)
	s_barrier
	s_waitcnt vmcnt(6)
	s_cmpk_lt_u32 s2, 0x100
	v_lshl_add_u32 v1, v13, 11, v1
	v_and_b32_e32 v2, 1, v12
	s_cselect_b64 s[42:43], -1, 0
	v_lshl_or_b32 v213, s1, 6, v0
	v_and_b32_e32 v216, 1, v8
	v_cndmask_b32_e64 v188, 1.0, -1.0, vcc
	v_lshl_or_b32 v1, v2, 6, v1
	s_add_i32 s59, 0, 0x10000
	s_add_i32 s65, 0, 0x14000
	v_lshlrev_b32_e32 v221, 2, v0
	v_mbcnt_lo_u32_b32 v0, -1, 0
	v_or_b32_e32 v214, 0xfffffc00, v213
	v_cmp_eq_u32_e64 s[4:5], 0, v216
	v_lshlrev_b32_e32 v186, 5, v216
	v_mov_b32_e32 v189, v188
	v_mov_b32_e32 v190, v188
	v_mov_b32_e32 v191, v188
	v_mov_b32_e32 v193, v185
	v_lshl_add_u32 v194, v14, 1, v1
	v_mov_b32_e32 v195, v185
	v_mov_b64_e32 v[196:197], 0x500
	v_mov_b64_e32 v[198:199], 0x4ff
	v_add_u32_e32 v218, s59, v212
	v_add_u32_e32 v219, s65, v212
	v_add_u32_e32 v220, 0, v4
	v_mov_b32_e32 v222, 0x358637bd
	s_mov_b64 s[70:71], 0x1000
	s_movk_i32 s84, 0x1000
	v_mbcnt_hi_u32_b32 v223, -1, v0
	v_mov_b32_e32 v224, 0x3e38aa3b
	v_mov_b32_e32 v225, 0x800
	s_barrier
	s_mov_b32 s98, 0
	s_branch .LBB0_199

.LBB0_636:
	s_mov_b64 s[24:25], 0x80
	s_and_b32 s48, s0, 3
	s_add_i32 m0, s3, 0x18000
	v_lshl_add_u64 v[6:7], v[6:7], 0, s[24:25]
	s_lshl_b32 s0, s1, 13
	s_lshl_b32 s7, s48, 12
	global_load_lds_dwordx4 v[6:7], off
	v_lshl_add_u64 v[4:5], v[4:5], 0, s[24:25]
	s_add_i32 m0, s3, 0x1a000
	s_add_i32 s49, s3, 0x8000
	s_add_i32 s50, s3, 0xa000
	global_load_lds_dwordx4 v[4:5], off
	v_lshl_add_u64 v[0:1], v[0:1], 0, s[24:25]
	s_mov_b32 m0, s49
	s_add_u32 s8, s44, 0x40080
	global_load_lds_dwordx4 v[0:1], off
	v_lshl_add_u64 v[0:1], v[2:3], 0, s[24:25]
	s_mov_b32 m0, s50
	s_addc_u32 s9, s45, 0
	global_load_lds_dwordx4 v[0:1], off
	s_add_i32 m0, s3, 0x1c000
	v_lshl_add_u64 v[0:1], s[8:9], 0, v[186:187]
	global_load_lds_dwordx4 v[0:1], off
	v_lshl_add_u64 v[0:1], s[8:9], 0, v[190:191]
	s_add_i32 m0, s3, 0x1e000
	s_cmpk_lt_u32 s6, 0x100
	global_load_lds_dwordx4 v[0:1], off
	v_bfe_u32 v1, v8, 4, 2
	v_and_b32_e32 v0, 15, v8
	v_lshlrev_b32_e32 v3, 4, v1
	v_lshl_or_b32 v207, s1, 6, v0
	v_lshl_or_b32 v0, v0, 6, v3
	v_lshlrev_b32_e32 v3, 2, v8
	v_and_b32_e32 v3, 32, v3
	v_lshlrev_b32_e32 v2, 3, v1
	v_bitop3_b32 v4, v0, s0, v3 bitop3:0xde
	v_cmp_eq_u32_e64 s[0:1], 0, v1
	v_lshlrev_b32_e32 v1, 14, v9
	v_and_b32_e32 v1, 0xffff8000, v1
	v_lshl_or_b32 v227, s48, 6, v2
	v_lshl_add_u32 v1, v10, 11, v1
	v_and_b32_e32 v2, 1, v9
	v_lshl_or_b32 v1, v2, 6, v1
	v_lshl_add_u32 v194, v11, 1, v1
	v_lshlrev_b32_e32 v1, 14, v12
	v_and_b32_e32 v1, 0xffff8000, v1
	s_waitcnt vmcnt(8)
	s_barrier
	s_waitcnt vmcnt(6)
	v_and_b32_e32 v233, 1, v8
	v_lshl_add_u32 v1, v13, 11, v1
	v_and_b32_e32 v2, 1, v12
	v_bitop3_b32 v211, v0, s7, v3 bitop3:0xde
	s_cselect_b64 s[26:27], -1, 0
	v_lshlrev_b32_e32 v0, 5, v233
	v_lshl_or_b32 v1, v2, 6, v1
	s_add_i32 s51, 0, 0x10000
	s_add_i32 s52, 0, 0x14000
	v_cmp_eq_u32_e64 s[6:7], 0, v233
	v_mov_b32_e32 v195, v193
	v_lshl_add_u32 v196, v14, 1, v1
	v_mov_b32_e32 v197, v193
	v_mov_b64_e32 v[198:199], 0x200
	v_mov_b64_e32 v[200:201], 0x1ff
	v_add_u32_e32 v236, s51, v211
	v_add_u32_e32 v237, s52, v211
	v_add_u32_e32 v238, 0, v4
	v_lshlrev_b32_e32 v192, 1, v0
	s_mov_b32 s53, 0
	s_barrier
	s_mov_b32 s98, 0
	s_branch .LBB0_639

.LBB0_741:
	s_and_b32 s22, s18, 3
	s_mov_b64 s[18:19], 0x80
	s_add_i32 m0, s31, 0x18000
	v_lshl_add_u64 v[6:7], v[6:7], 0, s[18:19]
	s_lshl_b32 s1, s6, 13
	s_lshl_b32 s23, s22, 12
	global_load_lds_dwordx4 v[6:7], off
	v_lshl_add_u64 v[4:5], v[4:5], 0, s[18:19]
	s_add_i32 m0, s31, 0x1a000
	s_add_i32 s44, s31, 0x8000
	s_add_i32 s45, s31, 0xa000
	global_load_lds_dwordx4 v[4:5], off
	v_lshl_add_u64 v[0:1], v[0:1], 0, s[18:19]
	s_mov_b32 m0, s44
	s_add_u32 s20, s38, 0x40080
	global_load_lds_dwordx4 v[0:1], off
	v_lshl_add_u64 v[0:1], v[2:3], 0, s[18:19]
	s_mov_b32 m0, s45
	s_addc_u32 s21, s39, 0
	global_load_lds_dwordx4 v[0:1], off
	s_add_i32 m0, s31, 0x1c000
	v_lshl_add_u64 v[0:1], s[20:21], 0, v[132:133]
	global_load_lds_dwordx4 v[0:1], off
	v_lshl_add_u64 v[0:1], s[20:21], 0, v[128:129]
	s_add_i32 m0, s31, 0x1e000
	s_sext_i32_i8 s49, s0
	global_load_lds_dwordx4 v[0:1], off
	v_lshrrev_b32_e32 v1, 1, v8
	v_and_b32_e32 v1, 24, v1
	v_and_b32_e32 v0, 15, v8
	v_lshlrev_b32_e32 v2, 1, v1
	v_lshl_or_b32 v2, v0, 6, v2
	v_lshlrev_b32_e32 v0, 2, v0
	v_and_b32_e32 v3, 32, v0
	v_lshl_or_b32 v151, s22, 6, v1
	v_lshlrev_b32_e32 v1, 14, v13
	v_bitop3_b32 v4, v2, s1, v3 bitop3:0xde
	v_bitop3_b32 v148, v2, s23, v3 bitop3:0xde
	v_and_b32_e32 v2, 14, v8
	v_and_b32_e32 v1, 0xffff8000, v1
	v_lshl_or_b32 v150, s6, 6, v2
	v_lshl_add_u32 v1, v12, 11, v1
	v_and_b32_e32 v2, 1, v13
	s_lshl_b32 s0, s6, 8
	v_lshl_or_b32 v1, v2, 6, v1
	s_add_i32 s0, s0, 0
	v_lshl_add_u32 v138, v14, 1, v1
	v_lshlrev_b32_e32 v1, 14, v9
	s_add_i32 s0, s0, 0x20000
	v_and_b32_e32 v1, 0xffff8000, v1
	s_waitcnt vmcnt(8)
	s_barrier
	s_waitcnt vmcnt(6)
	v_add_u32_e32 v149, s0, v0
	s_cmpk_lt_u32 s7, 0x100
	v_and_b32_e32 v0, 1, v8
	v_lshl_add_u32 v1, v10, 11, v1
	v_and_b32_e32 v2, 1, v9
	s_cselect_b64 s[20:21], -1, 0
	v_cmp_eq_u32_e64 s[0:1], 0, v0
	v_lshlrev_b32_e32 v0, 5, v0
	v_lshl_or_b32 v1, v2, 6, v1
	s_add_i32 s47, 0, 0x10000
	s_add_i32 s48, 0, 0x14000
	s_mov_b32 s46, 0
	v_mov_b32_e32 v139, v137
	v_lshl_add_u32 v140, v11, 1, v1
	v_mov_b32_e32 v141, v137
	v_mov_b64_e32 v[142:143], 0x800
	v_mov_b64_e32 v[144:145], 0x7ff
	v_add_u32_e32 v152, s47, v148
	v_add_u32_e32 v153, s48, v148
	v_add_u32_e32 v154, 0, v4
	v_lshlrev_b32_e32 v136, 1, v0
	s_barrier
	s_mov_b32 s98, 0
	s_branch .LBB0_744

.LBB0_818:
	s_lshl_b32 s5, s5, 5
	s_mov_b64 s[8:9], 0x80
	s_and_b32 s5, s5, 0x60
	s_add_i32 m0, s2, 0x18000
	v_lshl_add_u64 v[6:7], v[6:7], 0, s[8:9]
	s_lshl_b32 s16, s1, 13
	s_lshl_b32 s17, s5, 7
	global_load_lds_dwordx4 v[6:7], off
	v_lshl_add_u64 v[4:5], v[4:5], 0, s[8:9]
	s_add_i32 m0, s2, 0x1a000
	s_add_i32 s44, s2, 0x8000
	s_add_i32 s45, s2, 0xa000
	global_load_lds_dwordx4 v[4:5], off
	v_lshl_add_u64 v[0:1], v[0:1], 0, s[8:9]
	s_mov_b32 m0, s44
	s_add_u32 s10, s40, 0x100080
	global_load_lds_dwordx4 v[0:1], off
	v_lshl_add_u64 v[0:1], v[2:3], 0, s[8:9]
	s_mov_b32 m0, s45
	s_addc_u32 s11, s41, 0
	global_load_lds_dwordx4 v[0:1], off
	s_add_i32 m0, s2, 0x1c000
	v_lshl_add_u64 v[0:1], s[10:11], 0, v[128:129]
	global_load_lds_dwordx4 v[0:1], off
	v_lshl_add_u64 v[0:1], s[10:11], 0, v[130:131]
	s_add_i32 m0, s2, 0x1e000
	s_cmpk_lt_u32 s4, 0x100
	global_load_lds_dwordx4 v[0:1], off
	v_bfe_u32 v1, v215, 4, 2
	v_and_b32_e32 v0, 15, v215
	v_lshlrev_b32_e32 v2, 4, v1
	v_lshl_or_b32 v133, s1, 6, v0
	v_lshl_or_b32 v0, v0, 6, v2
	v_lshlrev_b32_e32 v2, 2, v215
	v_and_b32_e32 v2, 32, v2
	v_bitop3_b32 v3, v0, s16, v2 bitop3:0xde
	v_bitop3_b32 v192, v0, s17, v2 bitop3:0xde
	v_lshlrev_b32_e32 v0, 16, v8
	v_and_b32_e32 v0, 0xfffe0000, v0
	v_lshl_or_b32 v194, v1, 2, s5
	v_lshl_add_u32 v0, v9, 13, v0
	v_and_b32_e32 v1, 1, v8
	v_lshl_or_b32 v0, v1, 6, v0
	v_lshl_add_u32 v134, v10, 1, v0
	v_lshlrev_b32_e32 v0, 16, v11
	v_and_b32_e32 v0, 0xfffe0000, v0
	s_waitcnt vmcnt(8)
	s_barrier
	s_waitcnt vmcnt(6)
	v_lshl_add_u32 v0, v12, 13, v0
	v_and_b32_e32 v1, 1, v11
	s_cselect_b64 s[10:11], -1, 0
	v_and_b32_e32 v193, 1, v215
	v_lshl_or_b32 v0, v1, 6, v0
	s_add_i32 s46, 0, 0x10000
	s_add_i32 s47, 0, 0x14000
	s_sext_i32_i8 s53, s0
	v_cmp_eq_u32_e64 s[0:1], 0, v193
	v_lshlrev_b32_e32 v132, 4, v193
	v_mov_b32_e32 v135, v129
	v_lshl_add_u32 v136, v13, 1, v0
	v_mov_b32_e32 v137, v129
	v_mov_b64_e32 v[138:139], 0x200
	v_mov_b64_e32 v[140:141], 0x1ff
	v_add_u32_e32 v195, s46, v192
	v_add_u32_e32 v196, s47, v192
	v_add_u32_e32 v197, 0, v3
	s_mov_b64 s[16:17], 0x40000
	s_mov_b32 s48, 0x40000
	s_mov_b64 s[18:19], 0x48000
	s_mov_b32 s49, 0x48000
	s_mov_b64 s[20:21], 0x50000
	s_mov_b32 s50, 0x50000
	s_mov_b64 s[22:23], 0x58000
	s_mov_b32 s51, 0x58000
	s_movk_i32 s52, 0x1000
	s_barrier
	s_mov_b32 s98, 0
	s_branch .LBB0_821
